# P1/P5: the trailing wave group's re-stagger barrier moved from before the tile header to after it (header and accumulator zeroing now run while it would otherwise wait)
# baseline (speedup 1.0000x reference)
; #define PG8_STAGE(bufoff, gbase, voff) do { _Pragma("unroll") for (int _i = 0; _i < 2; ++_i) \
;         __builtin_amdgcn_global_load_lds((const __attribute__((address_space(1))) unsigned*)((const char*)(gbase) + (voff)[_i]), (LAS unsigned*)(lds + (bufoff) + ldsw + _i * 8192), 16, 0, 0); } while (0)
; #define PG8_WAIT_V(n) asm volatile("s_waitcnt vmcnt(" #n ")" ::: "memory")
; #define PG8_BAR __builtin_amdgcn_s_barrier()
; template <class Epi, class SchedT, bool ALIGN_EPI, bool SP2>
; __device__ __forceinline__ void gemm_phase(LAS unsigned char* lds, const int ldk, const int nt, const SchedT& S, const Epi& E) {
;     ...
;     if constexpr (SP2) {
;         PG8_STAGE(PG8_SB(0, 0), cB, voffB); PG8_STAGE(PG8_SB(0, 1), cB + hstepB, voffB); PG8_STAGE(PG8_SA(0, 0), cA, voffA); PG8_STAGE(PG8_SA(0, 1), cA + hstep, voffA);
;         if (wr == 1) PG8_BAR;
;         PG8_WAIT_V(2); PG8_BAR;
;         PG8_STAGE(PG8_SB(1, 0), cB + kstep, voffB); PG8_STAGE(PG8_SA(1, 0), cA + kstep, voffA); PG8_STAGE(PG8_SB(1, 1), cB + hstepB + kstep, voffB);
;         PG8_WAIT_V(6); PG8_BAR;
;     } else {
;         PG8_STAGE(PG8_SB(0, 0), cB, voffB); PG8_STAGE(PG8_SA(0, 0), cA, voffA); PG8_STAGE(PG8_SB(0, 1), cB + hstepB, voffB); PG8_STAGE(PG8_SA(0, 1), cA + hstep, voffA);
;         if (wr == 1) PG8_BAR;
;         PG8_WAIT_V(4); PG8_BAR;
;         PG8_STAGE(PG8_SB(1, 0), cB + kstep, voffB); PG8_STAGE(PG8_SA(1, 0), cA + kstep, voffA); PG8_STAGE(PG8_SB(1, 1), cB + hstepB + kstep, voffB);
;         PG8_WAIT_V(6); PG8_BAR;
;     }
;     for (;;) {
;         const bool has_next = S.next(ui + 1, nxt);
;         const char* nA = cA; const char* nB = cB; if (has_next) S.ptrs(nxt, nA, nB);
.LBB0_115:
	v_readlane_b32 s30, v163, 37
	v_readlane_b32 s31, v163, 38
	s_lshl_b64 s[30:31], s[30:31], 2
	s_add_u32 s1, s44, s30
	s_addc_u32 s19, s45, s31
	s_add_u32 s30, s1, 0x27c00000
	s_addc_u32 s31, s19, 0
	s_add_u32 s48, s44, 0x16c00000
	s_addc_u32 s49, s45, 0
	s_add_u32 s74, s44, 0x17c00000
	s_addc_u32 s75, s45, 0
	s_add_u32 s34, s44, 0x18c00000
	s_addc_u32 s35, s45, 0
	v_writelane_b32 v163, s34, 43
	s_add_u32 s54, s44, 0x1bc00000
	s_addc_u32 s55, s45, 0
	v_writelane_b32 v163, s35, 44
	v_lshl_add_u64 v[8:9], v[8:9], 0, s[24:25]
	v_readlane_b32 s34, v163, 41
	v_readlane_b32 s35, v163, 42
	s_lshl_b64 s[34:35], s[34:35], 2
	s_add_u32 s1, s44, s34
	s_addc_u32 s19, s45, s35
	s_add_u32 s56, s1, 0x28100000
	s_addc_u32 s57, s19, 0
	s_and_b32 s19, s0, 3
	s_add_i32 m0, s88, 0x18000
	s_lshl_b32 s21, s94, 13
	s_lshl_b32 s34, s19, 12
	s_waitcnt vmcnt(2)
	s_barrier
	global_load_lds_dwordx4 v[8:9], off
	v_lshl_add_u64 v[6:7], v[6:7], 0, s[24:25]
	s_add_i32 m0, s88, 0x1a000
	s_add_i32 s92, s88, 0x8000
	s_add_i32 s93, s88, 0xa000
	global_load_lds_dwordx4 v[6:7], off
	v_lshl_add_u64 v[2:3], v[2:3], 0, s[24:25]
	s_mov_b32 m0, s92
	s_add_u32 s0, s16, 0x20080
	global_load_lds_dwordx4 v[2:3], off
	v_lshl_add_u64 v[2:3], v[4:5], 0, s[24:25]
	s_mov_b32 m0, s93
	s_addc_u32 s1, s17, 0
	global_load_lds_dwordx4 v[2:3], off
	s_add_i32 m0, s88, 0x1c000
	v_lshl_add_u64 v[2:3], s[0:1], 0, v[158:159]
	global_load_lds_dwordx4 v[2:3], off
	v_lshl_add_u64 v[2:3], s[0:1], 0, v[174:175]
	s_add_i32 m0, s88, 0x1e000
	v_and_b32_e32 v210, 15, v0
	global_load_lds_dwordx4 v[2:3], off
	v_bfe_u32 v2, v0, 4, 2
	v_lshlrev_b32_e32 v5, 2, v0
	v_and_b32_e32 v213, 7, v0
	v_lshlrev_b32_e32 v0, 3, v0
	v_and_b32_e32 v0, 64, v0
	v_lshl_add_u64 v[176:177], s[30:31], 0, v[0:1]
	v_lshlrev_b32_e32 v0, 5, v2
	v_lshl_add_u64 v[178:179], s[30:31], 0, v[0:1]
	v_lshlrev_b32_e32 v0, 15, v10
	v_and_b32_e32 v0, 0xffff0000, v0
	v_lshlrev_b32_e32 v3, 3, v2
	v_lshlrev_b32_e32 v4, 4, v2
	v_lshlrev_b32_e32 v214, 6, v2
	v_lshl_add_u32 v0, v11, 12, v0
	v_and_b32_e32 v2, 1, v10
	v_lshl_or_b32 v0, v2, 6, v0
	v_lshl_add_u32 v180, v12, 1, v0
	v_lshlrev_b32_e32 v0, 15, v13
	v_and_b32_e32 v0, 0xffff0000, v0
	v_lshl_or_b32 v4, v210, 6, v4
	v_and_b32_e32 v5, 32, v5
	s_waitcnt vmcnt(6)
	v_lshl_add_u32 v0, v14, 12, v0
	v_and_b32_e32 v2, 1, v13
	v_bitop3_b32 v6, v4, s21, v5 bitop3:0xde
	s_cmpk_lt_u32 s18, 0x100
	v_lshl_or_b32 v0, v2, 6, v0
	v_lshl_or_b32 v211, s94, 6, v210
	v_bitop3_b32 v212, v4, s34, v5 bitop3:0xde
	s_cselect_b64 s[58:59], -1, 0
	s_add_i32 s94, s94, -8
	v_lshl_or_b32 v215, s19, 6, v3
	v_mov_b32_e32 v181, v1
	v_lshl_add_u32 v182, v15, 1, v0
	v_mov_b32_e32 v183, v1
	s_mov_b32 s95, 0
	v_add_u32_e32 v216, 0, v6
	s_mov_b32 s64, 0x503ce6da
	s_barrier
	s_mov_b32 s32, 0
	s_branch .LBB0_118

; #define PG8_STAGE(bufoff, gbase, voff) do { _Pragma("unroll") for (int _i = 0; _i < 2; ++_i) \
;         __builtin_amdgcn_global_load_lds((const __attribute__((address_space(1))) unsigned*)((const char*)(gbase) + (voff)[_i]), (LAS unsigned*)(lds + (bufoff) + ldsw + _i * 8192), 16, 0, 0); } while (0)
; #define PG8_LDA(dst, b, h) do { _Pragma("unroll") for (int m = 0; m < 4; ++m) _Pragma("unroll") for (int k = 0; k < 2; ++k) dst[m][k] = *(const LAS bf16x8*)(lds + PG8_SA(b, h) + aoff + m * 2048 + k * 1024); } while (0)
; #define PG8_LDB(dst, b, h) do { _Pragma("unroll") for (int n = 0; n < 2; ++n) _Pragma("unroll") for (int k = 0; k < 2; ++k) dst[n][k] = *(const LAS bf16x8*)(lds + PG8_SB(b, h) + boff + n * 2048 + k * 1024); } while (0)
; #define PG8_MMA(ai, bj, At, Bt) do { __builtin_amdgcn_s_setprio(1); _Pragma("unroll") for (int m = 0; m < 4; ++m) _Pragma("unroll") for (int n = 0; n < 2; ++n) _Pragma("unroll") for (int k = 0; k < 2; ++k) \
;         acc[ai][bj][m][n] = __builtin_amdgcn_mfma_f32_16x16x32_bf16(Bt[n][k], At[m][k], acc[ai][bj][m][n], 0, 0, 0); __builtin_amdgcn_s_setprio(0); } while (0)
; #define PG8_WAIT_V(n) asm volatile("s_waitcnt vmcnt(" #n ")" ::: "memory")
; #define PG8_WAIT_L(n) asm volatile("s_waitcnt lgkmcnt(" #n ")" ::: "memory")
; #define PG8_BAR __builtin_amdgcn_s_barrier()
; #define PG8_SCHED __builtin_amdgcn_sched_barrier(0)
; template <class Epi, class SchedT, bool ALIGN_EPI, bool SP2>
; __device__ __forceinline__ void gemm_phase(LAS unsigned char* lds, const int ldk, const int nt, const SchedT& S, const Epi& E) {
;     ...
;             PG8_LDB(B0, 0, 0); PG8_LDB(B1, 0, 1); PG8_SCHED; PG8_LDA(At, 0, 0); PG8_STAGE(PG8_SA(1, 1), a1 + hstep, voffA);
;             PG8_WAIT_V(8); PG8_WAIT_L(0); PG8_BAR; PG8_MMA(0, 0, At, B0); PG8_MMA(0, 1, At, B1); PG8_BAR; PG8_SCHED;
;     ...
; #pragma unroll
;         for (int a = 0; a < 2; ++a)
; #pragma unroll
;             for (int b = 0; b < 2; ++b)
; #pragma unroll
;                 for (int m = 0; m < 4; ++m)
; #pragma unroll
;                     for (int n = 0; n < 2; ++n) acc[a][b][m][n] = (f32x4){0.f, 0.f, 0.f, 0.f};
.LBB0_122:
	s_add_u32 s0, s12, 0x80080
	s_addc_u32 s1, s13, 0
	s_add_u32 s18, s16, 0x100
	v_mov_b64_e32 v[4:5], 0
	s_addc_u32 s19, s17, 0
	s_mov_b32 s21, -2
	v_mov_b64_e32 v[6:7], 0
	v_mov_b64_e32 v[8:9], 0
	v_mov_b64_e32 v[10:11], 0
	v_mov_b64_e32 v[20:21], 0
	v_mov_b64_e32 v[22:23], 0
	v_mov_b64_e32 v[24:25], 0
	v_mov_b64_e32 v[26:27], 0
	v_mov_b64_e32 v[36:37], 0
	v_mov_b64_e32 v[38:39], 0
	v_mov_b64_e32 v[40:41], 0
	v_mov_b64_e32 v[42:43], 0
	v_mov_b64_e32 v[52:53], 0
	v_mov_b64_e32 v[54:55], 0
	v_mov_b64_e32 v[56:57], 0
	v_mov_b64_e32 v[58:59], 0
	v_mov_b64_e32 v[12:13], 0
	v_mov_b64_e32 v[14:15], 0
	v_mov_b64_e32 v[16:17], 0
	v_mov_b64_e32 v[18:19], 0
	v_mov_b64_e32 v[28:29], 0
	v_mov_b64_e32 v[30:31], 0
	v_mov_b64_e32 v[32:33], 0
	v_mov_b64_e32 v[34:35], 0
	v_mov_b64_e32 v[44:45], 0
	v_mov_b64_e32 v[46:47], 0
	v_mov_b64_e32 v[48:49], 0
	v_mov_b64_e32 v[50:51], 0
	v_mov_b64_e32 v[60:61], 0
	v_mov_b64_e32 v[62:63], 0
	v_mov_b64_e32 v[64:65], 0
	v_mov_b64_e32 v[66:67], 0
	v_mov_b64_e32 v[68:69], 0
	v_mov_b64_e32 v[70:71], 0
	v_mov_b64_e32 v[72:73], 0
	v_mov_b64_e32 v[74:75], 0
	v_mov_b64_e32 v[84:85], 0
	v_mov_b64_e32 v[86:87], 0
	v_mov_b64_e32 v[88:89], 0
	v_mov_b64_e32 v[90:91], 0
	v_mov_b64_e32 v[100:101], 0
	v_mov_b64_e32 v[102:103], 0
	v_mov_b64_e32 v[104:105], 0
	v_mov_b64_e32 v[106:107], 0
	v_mov_b64_e32 v[116:117], 0
	v_mov_b64_e32 v[118:119], 0
	v_mov_b64_e32 v[120:121], 0
	v_mov_b64_e32 v[122:123], 0
	v_mov_b64_e32 v[76:77], 0
	v_mov_b64_e32 v[78:79], 0
	v_mov_b64_e32 v[80:81], 0
	v_mov_b64_e32 v[82:83], 0
	v_mov_b64_e32 v[92:93], 0
	v_mov_b64_e32 v[94:95], 0
	v_mov_b64_e32 v[96:97], 0
	v_mov_b64_e32 v[98:99], 0
	v_mov_b64_e32 v[108:109], 0
	v_mov_b64_e32 v[110:111], 0
	v_mov_b64_e32 v[112:113], 0
	v_mov_b64_e32 v[114:115], 0
	v_mov_b64_e32 v[124:125], 0
	v_mov_b64_e32 v[126:127], 0
	v_mov_b64_e32 v[128:129], 0
	v_mov_b64_e32 v[130:131], 0
	s_cmp_eq_u32 s32, 0
	s_cbranch_scc1 .Lp1_nostag
	s_mov_b32 s32, 0
	s_barrier
.Lp1_nostag:
.LBB0_123:
	s_add_u32 s12, s0, 0xfff80080
	s_addc_u32 s13, s1, -1
	s_add_i32 s34, 0, 0x10000
	s_cmp_eq_u32 s21, 28
	s_cselect_b32 s17, s61, s13
	s_cselect_b32 s16, s60, s12
	v_add_u32_e32 v0, s34, v212
	s_cselect_b32 s13, s31, s19
	s_cselect_b32 s12, s30, s18
	s_add_i32 s38, 0, 0x14000
	s_waitcnt lgkmcnt(0)
	ds_read_b128 v[132:135], v0
	ds_read_b128 v[136:139], v0 offset:1024
	ds_read_b128 v[140:143], v0 offset:2048
	ds_read_b128 v[144:147], v0 offset:3072
	v_add_u32_e32 v0, s38, v212
	ds_read_b128 v[148:151], v0
	ds_read_b128 v[152:155], v0 offset:1024
	ds_read_b128 v[184:187], v0 offset:2048
	ds_read_b128 v[188:191], v0 offset:3072
	v_lshl_add_u64 v[2:3], s[0:1], 0, v[180:181]
	s_add_i32 m0, s88, 0xc000
	ds_read_b128 v[192:195], v216
	ds_read_b128 v[196:199], v216 offset:1024
	ds_read_b128 v[200:203], v216 offset:2048
	ds_read_b128 v[204:207], v216 offset:3072
	ds_read_b128 v[218:221], v216 offset:4096
	ds_read_b128 v[222:225], v216 offset:5120
	ds_read_b128 v[226:229], v216 offset:6144
	ds_read_b128 v[230:233], v216 offset:7168
	global_load_lds_dwordx4 v[2:3], off
	v_lshl_add_u64 v[2:3], s[0:1], 0, v[182:183]
	s_add_i32 m0, s88, 0xe000
	s_nop 0
	global_load_lds_dwordx4 v[2:3], off
	s_waitcnt vmcnt(8)
	s_waitcnt lgkmcnt(0)
	s_barrier
	s_setprio 1
	s_waitcnt lgkmcnt(0)
	v_mfma_f32_16x16x32_bf16 v[128:131], v[132:135], v[192:195], v[128:131]
	v_mfma_f32_16x16x32_bf16 v[124:127], v[140:143], v[192:195], v[124:127]
	v_mfma_f32_16x16x32_bf16 v[112:115], v[132:135], v[200:203], v[112:115]
	v_mfma_f32_16x16x32_bf16 v[108:111], v[140:143], v[200:203], v[108:111]
	v_mfma_f32_16x16x32_bf16 v[96:99], v[132:135], v[218:221], v[96:99]
	v_mfma_f32_16x16x32_bf16 v[92:95], v[140:143], v[218:221], v[92:95]
	v_mfma_f32_16x16x32_bf16 v[80:83], v[132:135], v[226:229], v[80:83]
	v_mfma_f32_16x16x32_bf16 v[76:79], v[140:143], v[226:229], v[76:79]
	v_mfma_f32_16x16x32_bf16 v[128:131], v[136:139], v[196:199], v[128:131]
	v_mfma_f32_16x16x32_bf16 v[124:127], v[144:147], v[196:199], v[124:127]
	v_mfma_f32_16x16x32_bf16 v[112:115], v[136:139], v[204:207], v[112:115]
	v_mfma_f32_16x16x32_bf16 v[108:111], v[144:147], v[204:207], v[108:111]
	v_mfma_f32_16x16x32_bf16 v[96:99], v[136:139], v[222:225], v[96:99]
	v_mfma_f32_16x16x32_bf16 v[92:95], v[144:147], v[222:225], v[92:95]
	v_mfma_f32_16x16x32_bf16 v[80:83], v[136:139], v[230:233], v[80:83]
	v_mfma_f32_16x16x32_bf16 v[76:79], v[144:147], v[230:233], v[76:79]
	v_mfma_f32_16x16x32_bf16 v[120:123], v[148:151], v[192:195], v[120:123]
	v_mfma_f32_16x16x32_bf16 v[116:119], v[184:187], v[192:195], v[116:119]
	v_mfma_f32_16x16x32_bf16 v[104:107], v[148:151], v[200:203], v[104:107]
	v_mfma_f32_16x16x32_bf16 v[100:103], v[184:187], v[200:203], v[100:103]
	v_mfma_f32_16x16x32_bf16 v[88:91], v[148:151], v[218:221], v[88:91]
	v_mfma_f32_16x16x32_bf16 v[84:87], v[184:187], v[218:221], v[84:87]
	v_mfma_f32_16x16x32_bf16 v[72:75], v[148:151], v[226:229], v[72:75]
	v_mfma_f32_16x16x32_bf16 v[68:71], v[184:187], v[226:229], v[68:71]
	v_mfma_f32_16x16x32_bf16 v[120:123], v[152:155], v[196:199], v[120:123]
	v_mfma_f32_16x16x32_bf16 v[116:119], v[188:191], v[196:199], v[116:119]
	v_mfma_f32_16x16x32_bf16 v[104:107], v[152:155], v[204:207], v[104:107]
	v_mfma_f32_16x16x32_bf16 v[100:103], v[188:191], v[204:207], v[100:103]
	v_mfma_f32_16x16x32_bf16 v[88:91], v[152:155], v[222:225], v[88:91]
	v_mfma_f32_16x16x32_bf16 v[84:87], v[188:191], v[222:225], v[84:87]
	v_mfma_f32_16x16x32_bf16 v[72:75], v[152:155], v[230:233], v[72:75]
	v_mfma_f32_16x16x32_bf16 v[68:71], v[188:191], v[230:233], v[68:71]
	s_setprio 0
	s_barrier
; #define PG8_STAGE(bufoff, gbase, voff) do { _Pragma("unroll") for (int _i = 0; _i < 2; ++_i) \
;         __builtin_amdgcn_global_load_lds((const __attribute__((address_space(1))) unsigned*)((const char*)(gbase) + (voff)[_i]), (LAS unsigned*)(lds + (bufoff) + ldsw + _i * 8192), 16, 0, 0); } while (0)
; #define PG8_LDA(dst, b, h) do { _Pragma("unroll") for (int m = 0; m < 4; ++m) _Pragma("unroll") for (int k = 0; k < 2; ++k) dst[m][k] = *(const LAS bf16x8*)(lds + PG8_SA(b, h) + aoff + m * 2048 + k * 1024); } while (0)
; #define PG8_LDB(dst, b, h) do { _Pragma("unroll") for (int n = 0; n < 2; ++n) _Pragma("unroll") for (int k = 0; k < 2; ++k) dst[n][k] = *(const LAS bf16x8*)(lds + PG8_SB(b, h) + boff + n * 2048 + k * 1024); } while (0)
; #define PG8_MMA(ai, bj, At, Bt) do { __builtin_amdgcn_s_setprio(1); _Pragma("unroll") for (int m = 0; m < 4; ++m) _Pragma("unroll") for (int n = 0; n < 2; ++n) _Pragma("unroll") for (int k = 0; k < 2; ++k) \
;         acc[ai][bj][m][n] = __builtin_amdgcn_mfma_f32_16x16x32_bf16(Bt[n][k], At[m][k], acc[ai][bj][m][n], 0, 0, 0); __builtin_amdgcn_s_setprio(0); } while (0)
; #define PG8_WAIT_V(n) asm volatile("s_waitcnt vmcnt(" #n ")" ::: "memory")
; #define PG8_WAIT_L(n) asm volatile("s_waitcnt lgkmcnt(" #n ")" ::: "memory")
; #define PG8_BAR __builtin_amdgcn_s_barrier()
; #define PG8_SCHED __builtin_amdgcn_sched_barrier(0)
; template <class Epi, class SchedT, bool ALIGN_EPI, bool SP2>
; __device__ __forceinline__ void gemm_phase(LAS unsigned char* lds, const int ldk, const int nt, const SchedT& S, const Epi& E) {
;     ...
;             PG8_WAIT_V(8); PG8_WAIT_L(0); PG8_BAR; PG8_MMA(0, 0, At, B0); PG8_MMA(0, 1, At, B1); PG8_BAR; PG8_SCHED;
;             PG8_LDA(At, 0, 1); PG8_STAGE(PG8_SB(0, 0), b2, voffB); PG8_STAGE(PG8_SB(0, 1), b2 + hstepB, voffB); PG8_STAGE(PG8_SA(0, 0), a2, voffA);
;             PG8_WAIT_V(8); PG8_WAIT_L(0); PG8_BAR; PG8_MMA(1, 0, At, B0); PG8_MMA(1, 1, At, B1); PG8_BAR; PG8_SCHED;
;             PG8_LDB(B0, 1, 0); PG8_LDB(B1, 1, 1); PG8_SCHED; PG8_LDA(At, 1, 0); PG8_STAGE(PG8_SA(0, 1), a2 + hstep, voffA);
	s_add_i32 s34, s34, s87
	v_lshl_add_u64 v[208:209], s[12:13], 0, v[158:159]
	s_mov_b32 m0, s34
	ds_read_b128 v[192:195], v216 offset:16384
	ds_read_b128 v[196:199], v216 offset:17408
	ds_read_b128 v[200:203], v216 offset:18432
	ds_read_b128 v[204:207], v216 offset:19456
	ds_read_b128 v[218:221], v216 offset:20480
	ds_read_b128 v[222:225], v216 offset:21504
	ds_read_b128 v[226:229], v216 offset:22528
	ds_read_b128 v[230:233], v216 offset:23552
	global_load_lds_dwordx4 v[208:209], off
	s_add_i32 m0, s34, 0x2000
	s_add_u32 s34, s12, 0x20000
	v_lshl_add_u64 v[234:235], s[12:13], 0, v[174:175]
	s_addc_u32 s35, s13, 0
	s_add_i32 s38, s38, s87
	global_load_lds_dwordx4 v[234:235], off
	v_lshl_add_u64 v[2:3], s[34:35], 0, v[158:159]
	s_mov_b32 m0, s38
	v_lshl_add_u64 v[236:237], s[16:17], 0, v[156:157]
	global_load_lds_dwordx4 v[2:3], off
	v_lshl_add_u64 v[2:3], s[34:35], 0, v[174:175]
	s_add_i32 m0, s38, 0x2000
	v_lshl_add_u64 v[238:239], s[16:17], 0, v[160:161]
	global_load_lds_dwordx4 v[2:3], off
	s_mov_b32 m0, s88
	s_nop 0
	global_load_lds_dwordx4 v[236:237], off
	s_mov_b32 m0, s89
	s_nop 0
	global_load_lds_dwordx4 v[238:239], off
	s_waitcnt vmcnt(8)
	s_waitcnt lgkmcnt(0)
	s_barrier
	s_setprio 1
	s_waitcnt lgkmcnt(0)
	v_mfma_f32_16x16x32_bf16 v[64:67], v[132:135], v[192:195], v[64:67]
	v_mfma_f32_16x16x32_bf16 v[60:63], v[140:143], v[192:195], v[60:63]
	v_mfma_f32_16x16x32_bf16 v[48:51], v[132:135], v[200:203], v[48:51]
	v_mfma_f32_16x16x32_bf16 v[44:47], v[140:143], v[200:203], v[44:47]
	v_mfma_f32_16x16x32_bf16 v[32:35], v[132:135], v[218:221], v[32:35]
	v_mfma_f32_16x16x32_bf16 v[28:31], v[140:143], v[218:221], v[28:31]
	v_mfma_f32_16x16x32_bf16 v[16:19], v[132:135], v[226:229], v[16:19]
	v_mfma_f32_16x16x32_bf16 v[12:15], v[140:143], v[226:229], v[12:15]
	v_mfma_f32_16x16x32_bf16 v[64:67], v[136:139], v[196:199], v[64:67]
	v_mfma_f32_16x16x32_bf16 v[60:63], v[144:147], v[196:199], v[60:63]
	v_mfma_f32_16x16x32_bf16 v[48:51], v[136:139], v[204:207], v[48:51]
	v_mfma_f32_16x16x32_bf16 v[44:47], v[144:147], v[204:207], v[44:47]
	v_mfma_f32_16x16x32_bf16 v[32:35], v[136:139], v[222:225], v[32:35]
	v_mfma_f32_16x16x32_bf16 v[28:31], v[144:147], v[222:225], v[28:31]
	v_mfma_f32_16x16x32_bf16 v[16:19], v[136:139], v[230:233], v[16:19]
	v_mfma_f32_16x16x32_bf16 v[12:15], v[144:147], v[230:233], v[12:15]
	v_mfma_f32_16x16x32_bf16 v[56:59], v[148:151], v[192:195], v[56:59]
	v_mfma_f32_16x16x32_bf16 v[52:55], v[184:187], v[192:195], v[52:55]
	v_mfma_f32_16x16x32_bf16 v[40:43], v[148:151], v[200:203], v[40:43]
	v_mfma_f32_16x16x32_bf16 v[36:39], v[184:187], v[200:203], v[36:39]
	v_mfma_f32_16x16x32_bf16 v[24:27], v[148:151], v[218:221], v[24:27]
	v_mfma_f32_16x16x32_bf16 v[20:23], v[184:187], v[218:221], v[20:23]
	v_mfma_f32_16x16x32_bf16 v[8:11], v[148:151], v[226:229], v[8:11]
	v_mfma_f32_16x16x32_bf16 v[2:5], v[184:187], v[226:229], v[4:7]
	v_mfma_f32_16x16x32_bf16 v[56:59], v[152:155], v[196:199], v[56:59]
	v_mfma_f32_16x16x32_bf16 v[52:55], v[188:191], v[196:199], v[52:55]
	v_mfma_f32_16x16x32_bf16 v[40:43], v[152:155], v[204:207], v[40:43]
	v_mfma_f32_16x16x32_bf16 v[36:39], v[188:191], v[204:207], v[36:39]
	v_mfma_f32_16x16x32_bf16 v[24:27], v[152:155], v[222:225], v[24:27]
	v_mfma_f32_16x16x32_bf16 v[20:23], v[188:191], v[222:225], v[20:23]
	v_mfma_f32_16x16x32_bf16 v[8:11], v[152:155], v[230:233], v[8:11]
	v_mfma_f32_16x16x32_bf16 v[2:5], v[188:191], v[230:233], v[2:5]
	s_setprio 0
	s_barrier
	s_add_i32 s34, 0, 0x18000
	v_add_u32_e32 v0, s34, v212
	s_add_i32 s35, 0, 0x1c000
	ds_read_b128 v[132:135], v0
	ds_read_b128 v[136:139], v0 offset:1024
	ds_read_b128 v[140:143], v0 offset:2048
	ds_read_b128 v[144:147], v0 offset:3072
	v_add_u32_e32 v0, s35, v212
	ds_read_b128 v[148:151], v0
	ds_read_b128 v[152:155], v0 offset:1024
	ds_read_b128 v[184:187], v0 offset:2048
	ds_read_b128 v[188:191], v0 offset:3072
	s_add_u32 s16, s16, 0x80000
	s_addc_u32 s17, s17, 0
	s_mov_b32 m0, s90
	v_lshl_add_u64 v[6:7], s[16:17], 0, v[156:157]
	ds_read_b128 v[192:195], v216 offset:32768
	ds_read_b128 v[196:199], v216 offset:33792
	ds_read_b128 v[200:203], v216 offset:34816
	ds_read_b128 v[204:207], v216 offset:35840
	ds_read_b128 v[218:221], v216 offset:36864
	ds_read_b128 v[222:225], v216 offset:37888
	ds_read_b128 v[226:229], v216 offset:38912
	ds_read_b128 v[230:233], v216 offset:39936
	global_load_lds_dwordx4 v[6:7], off
	v_lshl_add_u64 v[6:7], s[16:17], 0, v[160:161]
	s_mov_b32 m0, s91
	s_nop 0
	global_load_lds_dwordx4 v[6:7], off
	s_waitcnt vmcnt(8)
	s_waitcnt lgkmcnt(0)
	s_barrier
; #define PG8_STAGE(bufoff, gbase, voff) do { _Pragma("unroll") for (int _i = 0; _i < 2; ++_i) \
;         __builtin_amdgcn_global_load_lds((const __attribute__((address_space(1))) unsigned*)((const char*)(gbase) + (voff)[_i]), (LAS unsigned*)(lds + (bufoff) + ldsw + _i * 8192), 16, 0, 0); } while (0)
; #define PG8_LDA(dst, b, h) do { _Pragma("unroll") for (int m = 0; m < 4; ++m) _Pragma("unroll") for (int k = 0; k < 2; ++k) dst[m][k] = *(const LAS bf16x8*)(lds + PG8_SA(b, h) + aoff + m * 2048 + k * 1024); } while (0)
; #define PG8_LDB(dst, b, h) do { _Pragma("unroll") for (int n = 0; n < 2; ++n) _Pragma("unroll") for (int k = 0; k < 2; ++k) dst[n][k] = *(const LAS bf16x8*)(lds + PG8_SB(b, h) + boff + n * 2048 + k * 1024); } while (0)
; #define PG8_MMA(ai, bj, At, Bt) do { __builtin_amdgcn_s_setprio(1); _Pragma("unroll") for (int m = 0; m < 4; ++m) _Pragma("unroll") for (int n = 0; n < 2; ++n) _Pragma("unroll") for (int k = 0; k < 2; ++k) \
;         acc[ai][bj][m][n] = __builtin_amdgcn_mfma_f32_16x16x32_bf16(Bt[n][k], At[m][k], acc[ai][bj][m][n], 0, 0, 0); __builtin_amdgcn_s_setprio(0); } while (0)
; #define PG8_WAIT_V(n) asm volatile("s_waitcnt vmcnt(" #n ")" ::: "memory")
; #define PG8_WAIT_L(n) asm volatile("s_waitcnt lgkmcnt(" #n ")" ::: "memory")
; #define PG8_BAR __builtin_amdgcn_s_barrier()
; #define PG8_SCHED __builtin_amdgcn_sched_barrier(0)
; template <class Epi, class SchedT, bool ALIGN_EPI, bool SP2>
; __device__ __forceinline__ void gemm_phase(LAS unsigned char* lds, const int ldk, const int nt, const SchedT& S, const Epi& E) {
;     ...
;             PG8_LDB(B0, 1, 0); PG8_LDB(B1, 1, 1); PG8_SCHED; PG8_LDA(At, 1, 0); PG8_STAGE(PG8_SA(0, 1), a2 + hstep, voffA);
;             PG8_WAIT_V(8); PG8_WAIT_L(0); PG8_BAR; PG8_MMA(0, 0, At, B0); PG8_MMA(0, 1, At, B1); PG8_BAR; PG8_SCHED;
;             PG8_LDA(At, 1, 1); PG8_STAGE(PG8_SB(1, 0), b3, voffB); PG8_STAGE(PG8_SB(1, 1), b3 + hstepB, voffB); PG8_STAGE(PG8_SA(1, 0), a3, voffA);
;             PG8_WAIT_V(8); PG8_WAIT_L(0); PG8_BAR; PG8_MMA(1, 0, At, B0); PG8_MMA(1, 1, At, B1); PG8_BAR; PG8_SCHED;
;     ...
;         if constexpr (ALIGN_EPI) { if (wr == 0) PG8_BAR; }
	s_setprio 1
	s_waitcnt lgkmcnt(0)
	v_mfma_f32_16x16x32_bf16 v[128:131], v[132:135], v[192:195], v[128:131]
	v_mfma_f32_16x16x32_bf16 v[124:127], v[140:143], v[192:195], v[124:127]
	v_mfma_f32_16x16x32_bf16 v[112:115], v[132:135], v[200:203], v[112:115]
	v_mfma_f32_16x16x32_bf16 v[108:111], v[140:143], v[200:203], v[108:111]
	v_mfma_f32_16x16x32_bf16 v[96:99], v[132:135], v[218:221], v[96:99]
	v_mfma_f32_16x16x32_bf16 v[92:95], v[140:143], v[218:221], v[92:95]
	v_mfma_f32_16x16x32_bf16 v[80:83], v[132:135], v[226:229], v[80:83]
	v_mfma_f32_16x16x32_bf16 v[76:79], v[140:143], v[226:229], v[76:79]
	v_mfma_f32_16x16x32_bf16 v[128:131], v[136:139], v[196:199], v[128:131]
	v_mfma_f32_16x16x32_bf16 v[124:127], v[144:147], v[196:199], v[124:127]
	v_mfma_f32_16x16x32_bf16 v[112:115], v[136:139], v[204:207], v[112:115]
	v_mfma_f32_16x16x32_bf16 v[108:111], v[144:147], v[204:207], v[108:111]
	v_mfma_f32_16x16x32_bf16 v[96:99], v[136:139], v[222:225], v[96:99]
	v_mfma_f32_16x16x32_bf16 v[92:95], v[144:147], v[222:225], v[92:95]
	v_mfma_f32_16x16x32_bf16 v[80:83], v[136:139], v[230:233], v[80:83]
	v_mfma_f32_16x16x32_bf16 v[76:79], v[144:147], v[230:233], v[76:79]
	v_mfma_f32_16x16x32_bf16 v[120:123], v[148:151], v[192:195], v[120:123]
	v_mfma_f32_16x16x32_bf16 v[116:119], v[184:187], v[192:195], v[116:119]
	v_mfma_f32_16x16x32_bf16 v[104:107], v[148:151], v[200:203], v[104:107]
	v_mfma_f32_16x16x32_bf16 v[100:103], v[184:187], v[200:203], v[100:103]
	v_mfma_f32_16x16x32_bf16 v[88:91], v[148:151], v[218:221], v[88:91]
	v_mfma_f32_16x16x32_bf16 v[84:87], v[184:187], v[218:221], v[84:87]
	v_mfma_f32_16x16x32_bf16 v[72:75], v[148:151], v[226:229], v[72:75]
	v_mfma_f32_16x16x32_bf16 v[68:71], v[184:187], v[226:229], v[68:71]
	v_mfma_f32_16x16x32_bf16 v[120:123], v[152:155], v[196:199], v[120:123]
	v_mfma_f32_16x16x32_bf16 v[116:119], v[188:191], v[196:199], v[116:119]
	v_mfma_f32_16x16x32_bf16 v[104:107], v[152:155], v[204:207], v[104:107]
	v_mfma_f32_16x16x32_bf16 v[100:103], v[188:191], v[204:207], v[100:103]
	v_mfma_f32_16x16x32_bf16 v[88:91], v[152:155], v[222:225], v[88:91]
	v_mfma_f32_16x16x32_bf16 v[84:87], v[188:191], v[222:225], v[84:87]
	v_mfma_f32_16x16x32_bf16 v[72:75], v[152:155], v[230:233], v[72:75]
	v_mfma_f32_16x16x32_bf16 v[68:71], v[188:191], v[230:233], v[68:71]
	s_setprio 0
	s_barrier
	s_add_i32 s16, s34, s87
	v_lshl_add_u64 v[6:7], v[208:209], 0, s[24:25]
	s_mov_b32 m0, s16
	ds_read_b128 v[192:195], v216 offset:49152
	ds_read_b128 v[196:199], v216 offset:50176
	ds_read_b128 v[200:203], v216 offset:51200
	ds_read_b128 v[204:207], v216 offset:52224
	ds_read_b128 v[218:221], v216 offset:53248
	ds_read_b128 v[222:225], v216 offset:54272
	ds_read_b128 v[226:229], v216 offset:55296
	ds_read_b128 v[230:233], v216 offset:56320
	global_load_lds_dwordx4 v[6:7], off
	s_add_i32 m0, s16, 0x2000
	s_add_u32 s12, s12, 0x20080
	v_lshl_add_u64 v[6:7], v[234:235], 0, s[24:25]
	s_addc_u32 s13, s13, 0
	s_add_i32 s16, s35, s87
	global_load_lds_dwordx4 v[6:7], off
	v_lshl_add_u64 v[6:7], s[12:13], 0, v[158:159]
	s_mov_b32 m0, s16
	s_nop 0
	global_load_lds_dwordx4 v[6:7], off
	v_lshl_add_u64 v[6:7], s[12:13], 0, v[174:175]
	s_add_i32 m0, s16, 0x2000
	s_nop 0
	global_load_lds_dwordx4 v[6:7], off
	v_lshl_add_u64 v[6:7], v[236:237], 0, s[24:25]
	s_mov_b32 m0, s92
	s_nop 0
	global_load_lds_dwordx4 v[6:7], off
	v_lshl_add_u64 v[6:7], v[238:239], 0, s[24:25]
	s_mov_b32 m0, s93
	s_nop 0
	global_load_lds_dwordx4 v[6:7], off
	s_waitcnt vmcnt(8)
	s_waitcnt lgkmcnt(0)
	s_barrier
	s_setprio 1
	s_waitcnt lgkmcnt(0)
	v_mfma_f32_16x16x32_bf16 v[64:67], v[132:135], v[192:195], v[64:67]
	v_mfma_f32_16x16x32_bf16 v[60:63], v[140:143], v[192:195], v[60:63]
	v_mfma_f32_16x16x32_bf16 v[48:51], v[132:135], v[200:203], v[48:51]
	v_mfma_f32_16x16x32_bf16 v[44:47], v[140:143], v[200:203], v[44:47]
	v_mfma_f32_16x16x32_bf16 v[32:35], v[132:135], v[218:221], v[32:35]
	v_mfma_f32_16x16x32_bf16 v[28:31], v[140:143], v[218:221], v[28:31]
	v_mfma_f32_16x16x32_bf16 v[16:19], v[132:135], v[226:229], v[16:19]
	v_mfma_f32_16x16x32_bf16 v[12:15], v[140:143], v[226:229], v[12:15]
	v_mfma_f32_16x16x32_bf16 v[64:67], v[136:139], v[196:199], v[64:67]
	v_mfma_f32_16x16x32_bf16 v[60:63], v[144:147], v[196:199], v[60:63]
	v_mfma_f32_16x16x32_bf16 v[48:51], v[136:139], v[204:207], v[48:51]
	v_mfma_f32_16x16x32_bf16 v[44:47], v[144:147], v[204:207], v[44:47]
	v_mfma_f32_16x16x32_bf16 v[32:35], v[136:139], v[222:225], v[32:35]
	v_mfma_f32_16x16x32_bf16 v[28:31], v[144:147], v[222:225], v[28:31]
	v_mfma_f32_16x16x32_bf16 v[16:19], v[136:139], v[230:233], v[16:19]
	v_mfma_f32_16x16x32_bf16 v[12:15], v[144:147], v[230:233], v[12:15]
	v_mfma_f32_16x16x32_bf16 v[56:59], v[148:151], v[192:195], v[56:59]
	v_mfma_f32_16x16x32_bf16 v[52:55], v[184:187], v[192:195], v[52:55]
	v_mfma_f32_16x16x32_bf16 v[40:43], v[148:151], v[200:203], v[40:43]
	v_mfma_f32_16x16x32_bf16 v[36:39], v[184:187], v[200:203], v[36:39]
	v_mfma_f32_16x16x32_bf16 v[24:27], v[148:151], v[218:221], v[24:27]
	v_mfma_f32_16x16x32_bf16 v[20:23], v[184:187], v[218:221], v[20:23]
	v_mfma_f32_16x16x32_bf16 v[6:9], v[148:151], v[226:229], v[8:11]
	v_mfma_f32_16x16x32_bf16 v[2:5], v[184:187], v[226:229], v[2:5]
	v_mfma_f32_16x16x32_bf16 v[56:59], v[152:155], v[196:199], v[56:59]
	v_mfma_f32_16x16x32_bf16 v[52:55], v[188:191], v[196:199], v[52:55]
	v_mfma_f32_16x16x32_bf16 v[40:43], v[152:155], v[204:207], v[40:43]
	v_mfma_f32_16x16x32_bf16 v[36:39], v[188:191], v[204:207], v[36:39]
	v_mfma_f32_16x16x32_bf16 v[24:27], v[152:155], v[222:225], v[24:27]
	v_mfma_f32_16x16x32_bf16 v[20:23], v[188:191], v[222:225], v[20:23]
	v_mfma_f32_16x16x32_bf16 v[8:11], v[152:155], v[230:233], v[6:9]
	v_mfma_f32_16x16x32_bf16 v[4:7], v[188:191], v[230:233], v[2:5]
	s_setprio 0
	s_barrier
	s_add_i32 s21, s21, 2
	s_add_u32 s0, s0, 0x100
	s_addc_u32 s1, s1, 0
	s_add_u32 s18, s18, 0x100
	s_addc_u32 s19, s19, 0
	s_cmp_gt_u32 s21, 29
	s_cbranch_scc0 .LBB0_123
	s_and_b64 vcc, exec, s[58:59]
	s_cbranch_vccz .LBB0_126
	s_barrier
	s_setprio 3

; #define PG8_BAR __builtin_amdgcn_s_barrier()
; template <class Epi, class SchedT, bool ALIGN_EPI, bool SP2>
; __device__ __forceinline__ void gemm_phase(LAS unsigned char* lds, const int ldk, const int nt, const SchedT& S, const Epi& E) {
;     ...
;         if constexpr (ALIGN_EPI) { if (wr == 0) PG8_BAR; }
;         E(acc, cur, wr, wc, fr, fq);
;         if (!has_next) break;
;         if (!(SchedT::kMode == 2 && cur.kind == 0)) {
; #pragma unroll
;         for (int a = 0; a < 2; ++a)
; #pragma unroll
;             for (int b = 0; b < 2; ++b)
; #pragma unroll
;                 for (int m = 0; m < 4; ++m)
; #pragma unroll
;                     for (int n = 0; n < 2; ++n) acc[a][b][m][n] = (f32x4){0.f, 0.f, 0.f, 0.f};
;         }
;         cur = nxt; cA = nA; cB = nB; ++ui;
;         if constexpr (ALIGN_EPI) { if (wr == 1) PG8_BAR; }
.LBB0_245:
.LBB0_246:
.LBB0_247:
.LBB0_249:
.LBB0_252:
.LBB0_253:
.LBB0_254:
.LBB0_256:
.LBB0_259:
.LBB0_260:
.LBB0_261:
.LBB0_263:
.LBB0_266:
.LBB0_267:
.LBB0_268:
.LBB0_270:
.LBB0_273:
.LBB0_274:
.LBB0_275:
.LBB0_277:
.LBB0_280:
.LBB0_281:
.LBB0_282:
.LBB0_284:
.LBB0_287:
.LBB0_288:
.LBB0_289:
.LBB0_291:
.LBB0_294:
.LBB0_295:
.LBB0_296:
.LBB0_298:
.LBB0_301:
.LBB0_302:
.LBB0_303:
.LBB0_305:
.LBB0_308:
.LBB0_309:
.LBB0_310:
.LBB0_312:
.LBB0_315:
.LBB0_316:
.LBB0_317:
.LBB0_319:
.LBB0_322:
.LBB0_323:
.LBB0_324:
.LBB0_326:
.LBB0_329:
.LBB0_330:
.LBB0_331:
.LBB0_333:
.LBB0_336:
.LBB0_337:
.LBB0_338:
.LBB0_340:
.LBB0_343:
.LBB0_344:
.LBB0_345:
.LBB0_347:
.LBB0_350:
.LBB0_351:
.LBB0_352:
.LBB0_354:
	s_and_b64 vcc, exec, s[36:37]
	s_mov_b64 s[0:1], -1
	s_cbranch_vccnz .LBB0_117
	s_cmp_lg_u64 s[46:47], 0
	s_cselect_b32 s32, 1, 0
	s_branch .LBB0_116

; #define PG8_STAGE(bufoff, gbase, voff) do { _Pragma("unroll") for (int _i = 0; _i < 2; ++_i) \
;         __builtin_amdgcn_global_load_lds((const __attribute__((address_space(1))) unsigned*)((const char*)(gbase) + (voff)[_i]), (LAS unsigned*)(lds + (bufoff) + ldsw + _i * 8192), 16, 0, 0); } while (0)
; #define PG8_WAIT_V(n) asm volatile("s_waitcnt vmcnt(" #n ")" ::: "memory")
; #define PG8_BAR __builtin_amdgcn_s_barrier()
; template <class Epi, class SchedT, bool ALIGN_EPI, bool SP2>
; __device__ __forceinline__ void gemm_phase(LAS unsigned char* lds, const int ldk, const int nt, const SchedT& S, const Epi& E) {
;     ...
;     if constexpr (SP2) {
;         PG8_STAGE(PG8_SB(0, 0), cB, voffB); PG8_STAGE(PG8_SB(0, 1), cB + hstepB, voffB); PG8_STAGE(PG8_SA(0, 0), cA, voffA); PG8_STAGE(PG8_SA(0, 1), cA + hstep, voffA);
;         if (wr == 1) PG8_BAR;
;         PG8_WAIT_V(2); PG8_BAR;
;         PG8_STAGE(PG8_SB(1, 0), cB + kstep, voffB); PG8_STAGE(PG8_SA(1, 0), cA + kstep, voffA); PG8_STAGE(PG8_SB(1, 1), cB + hstepB + kstep, voffB);
;         PG8_WAIT_V(6); PG8_BAR;
;     } else {
;         PG8_STAGE(PG8_SB(0, 0), cB, voffB); PG8_STAGE(PG8_SA(0, 0), cA, voffA); PG8_STAGE(PG8_SB(0, 1), cB + hstepB, voffB); PG8_STAGE(PG8_SA(0, 1), cA + hstep, voffA);
;         if (wr == 1) PG8_BAR;
;         PG8_WAIT_V(4); PG8_BAR;
;         PG8_STAGE(PG8_SB(1, 0), cB + kstep, voffB); PG8_STAGE(PG8_SA(1, 0), cA + kstep, voffA); PG8_STAGE(PG8_SB(1, 1), cB + hstepB + kstep, voffB);
;         PG8_WAIT_V(6); PG8_BAR;
;     }
;     for (;;) {
;         const bool has_next = S.next(ui + 1, nxt);
;         const char* nA = cA; const char* nB = cB; if (has_next) S.ptrs(nxt, nA, nB);
.LBB0_744:
	s_lshl_b64 s[0:1], s[30:31], 2
	s_add_u32 s0, s38, s0
	s_addc_u32 s1, s39, s1
	s_add_u32 s30, s38, 0x21800000
	v_lshrrev_b32_e32 v17, 1, v16
	s_addc_u32 s31, s39, 0
	v_and_b32_e32 v17, 24, v17
	s_add_u32 s54, s38, 0x28200000
	v_and_b32_e32 v246, 15, v16
	v_lshlrev_b32_e32 v18, 1, v17
	v_lshlrev_b32_e32 v16, 2, v16
	s_addc_u32 s55, s39, 0
	v_lshl_or_b32 v18, v246, 6, v18
	s_lshl_b32 s13, s50, 13
	v_and_b32_e32 v16, 32, v16
	v_bitop3_b32 v19, v18, s13, v16 bitop3:0xde
	s_lshl_b32 s13, s41, 5
	s_and_b32 s13, s13, 0x60
	s_add_i32 m0, s85, 0x18000
	v_lshl_add_u64 v[8:9], v[8:9], 0, s[24:25]
	s_lshl_b32 s17, s13, 7
	s_waitcnt vmcnt(2)
	s_barrier
	global_load_lds_dwordx4 v[8:9], off
	v_lshl_add_u64 v[6:7], v[6:7], 0, s[24:25]
	s_add_i32 m0, s85, 0x1a000
	s_add_i32 s89, s85, 0x8000
	s_add_i32 s90, s85, 0xa000
	global_load_lds_dwordx4 v[6:7], off
	v_lshl_add_u64 v[2:3], v[2:3], 0, s[24:25]
	s_mov_b32 m0, s89
	s_add_u32 s38, s36, 0x20080
	global_load_lds_dwordx4 v[2:3], off
	v_lshl_add_u64 v[2:3], v[4:5], 0, s[24:25]
	s_mov_b32 m0, s90
	s_addc_u32 s39, s37, 0
	global_load_lds_dwordx4 v[2:3], off
	s_add_i32 m0, s85, 0x1c000
	v_lshl_add_u64 v[2:3], s[38:39], 0, v[0:1]
	global_load_lds_dwordx4 v[2:3], off
	v_lshl_add_u64 v[2:3], s[38:39], 0, v[150:151]
	s_add_i32 m0, s85, 0x1e000
	s_cmpk_lt_u32 s40, 0x100
	global_load_lds_dwordx4 v[2:3], off
	v_lshlrev_b32_e32 v2, 2, v17
	v_mov_b32_e32 v3, v1
	v_lshl_add_u64 v[2:3], s[0:1], 0, v[2:3]
	s_mov_b64 s[0:1], 0x27c00000
	v_lshl_add_u64 v[152:153], v[2:3], 0, s[0:1]
	v_lshlrev_b32_e32 v2, 15, v10
	v_and_b32_e32 v2, 0xffff0000, v2
	v_lshl_add_u32 v2, v11, 12, v2
	v_and_b32_e32 v3, 1, v10
	v_lshl_or_b32 v2, v3, 6, v2
	v_lshl_add_u32 v154, v12, 1, v2
	v_lshlrev_b32_e32 v2, 15, v13
	v_and_b32_e32 v2, 0xffff0000, v2
	s_waitcnt vmcnt(6)
	v_lshl_add_u32 v2, v14, 12, v2
	v_and_b32_e32 v3, 1, v13
	v_lshl_or_b32 v2, v3, 6, v2
	v_lshl_or_b32 v247, s50, 6, v246
	v_bitop3_b32 v248, v18, s17, v16 bitop3:0xde
	s_cselect_b64 s[56:57], -1, 0
	v_cmp_eq_u32_e64 s[38:39], 15, v246
	v_cmp_ne_u32_e64 s[40:41], 15, v246
	s_mov_b32 s91, 0
	v_cmp_eq_u32_e64 s[42:43], 0, v246
	v_cmp_ne_u32_e64 s[44:45], 0, v246
	v_cmp_gt_u32_e64 s[46:47], 2, v246
	v_cmp_lt_u32_e64 s[48:49], 13, v246
	v_add_u32_e32 v249, -12, v246
	s_lshl_b32 s92, s50, 2
	v_or_b32_e32 v250, s13, v17
	v_mov_b32_e32 v155, v1
	v_lshl_add_u32 v156, v15, 1, v2
	v_mov_b32_e32 v157, v1
	v_add_u32_e32 v251, 0, v19
	s_movk_i32 s80, 0x5600
	s_barrier
	s_mov_b32 s32, 0
	s_branch .LBB0_747

; #define PG8_STAGE(bufoff, gbase, voff) do { _Pragma("unroll") for (int _i = 0; _i < 2; ++_i) \
;         __builtin_amdgcn_global_load_lds((const __attribute__((address_space(1))) unsigned*)((const char*)(gbase) + (voff)[_i]), (LAS unsigned*)(lds + (bufoff) + ldsw + _i * 8192), 16, 0, 0); } while (0)
; #define PG8_LDA(dst, b, h) do { _Pragma("unroll") for (int m = 0; m < 4; ++m) _Pragma("unroll") for (int k = 0; k < 2; ++k) dst[m][k] = *(const LAS bf16x8*)(lds + PG8_SA(b, h) + aoff + m * 2048 + k * 1024); } while (0)
; #define PG8_LDB(dst, b, h) do { _Pragma("unroll") for (int n = 0; n < 2; ++n) _Pragma("unroll") for (int k = 0; k < 2; ++k) dst[n][k] = *(const LAS bf16x8*)(lds + PG8_SB(b, h) + boff + n * 2048 + k * 1024); } while (0)
; #define PG8_MMA(ai, bj, At, Bt) do { __builtin_amdgcn_s_setprio(1); _Pragma("unroll") for (int m = 0; m < 4; ++m) _Pragma("unroll") for (int n = 0; n < 2; ++n) _Pragma("unroll") for (int k = 0; k < 2; ++k) \
;         acc[ai][bj][m][n] = __builtin_amdgcn_mfma_f32_16x16x32_bf16(Bt[n][k], At[m][k], acc[ai][bj][m][n], 0, 0, 0); __builtin_amdgcn_s_setprio(0); } while (0)
; #define PG8_WAIT_V(n) asm volatile("s_waitcnt vmcnt(" #n ")" ::: "memory")
; #define PG8_WAIT_L(n) asm volatile("s_waitcnt lgkmcnt(" #n ")" ::: "memory")
; #define PG8_BAR __builtin_amdgcn_s_barrier()
; #define PG8_SCHED __builtin_amdgcn_sched_barrier(0)
; template <class Epi, class SchedT, bool ALIGN_EPI, bool SP2>
; __device__ __forceinline__ void gemm_phase(LAS unsigned char* lds, const int ldk, const int nt, const SchedT& S, const Epi& E) {
;     ...
;             PG8_LDB(B0, 0, 0); PG8_LDB(B1, 0, 1); PG8_SCHED; PG8_LDA(At, 0, 0); PG8_STAGE(PG8_SA(1, 1), a1 + hstep, voffA);
;             PG8_WAIT_V(8); PG8_WAIT_L(0); PG8_BAR; PG8_MMA(0, 0, At, B0); PG8_MMA(0, 1, At, B1); PG8_BAR; PG8_SCHED;
;     ...
; #pragma unroll
;         for (int a = 0; a < 2; ++a)
; #pragma unroll
;             for (int b = 0; b < 2; ++b)
; #pragma unroll
;                 for (int m = 0; m < 4; ++m)
; #pragma unroll
;                     for (int n = 0; n < 2; ++n) acc[a][b][m][n] = (f32x4){0.f, 0.f, 0.f, 0.f};
.LBB0_751:
	s_add_u32 s34, s34, 0x80080
	s_addc_u32 s35, s35, 0
	s_add_u32 s13, s36, 0x100
	v_mov_b64_e32 v[2:3], 0
	s_addc_u32 s17, s37, 0
	s_mov_b32 s59, -2
	v_mov_b64_e32 v[4:5], 0
	v_mov_b64_e32 v[66:67], 0
	v_mov_b64_e32 v[68:69], 0
	v_mov_b64_e32 v[6:7], 0
	v_mov_b64_e32 v[8:9], 0
	v_mov_b64_e32 v[70:71], 0
	v_mov_b64_e32 v[72:73], 0
	v_mov_b64_e32 v[18:19], 0
	v_mov_b64_e32 v[20:21], 0
	v_mov_b64_e32 v[82:83], 0
	v_mov_b64_e32 v[84:85], 0
	v_mov_b64_e32 v[22:23], 0
	v_mov_b64_e32 v[24:25], 0
	v_mov_b64_e32 v[86:87], 0
	v_mov_b64_e32 v[88:89], 0
	v_mov_b64_e32 v[10:11], 0
	v_mov_b64_e32 v[12:13], 0
	v_mov_b64_e32 v[74:75], 0
	v_mov_b64_e32 v[76:77], 0
	v_mov_b64_e32 v[14:15], 0
	v_mov_b64_e32 v[16:17], 0
	v_mov_b64_e32 v[78:79], 0
	v_mov_b64_e32 v[80:81], 0
	v_mov_b64_e32 v[26:27], 0
	v_mov_b64_e32 v[28:29], 0
	v_mov_b64_e32 v[90:91], 0
	v_mov_b64_e32 v[92:93], 0
	v_mov_b64_e32 v[30:31], 0
	v_mov_b64_e32 v[32:33], 0
	v_mov_b64_e32 v[94:95], 0
	v_mov_b64_e32 v[96:97], 0
	v_mov_b64_e32 v[34:35], 0
	v_mov_b64_e32 v[36:37], 0
	v_mov_b64_e32 v[98:99], 0
	v_mov_b64_e32 v[100:101], 0
	v_mov_b64_e32 v[38:39], 0
	v_mov_b64_e32 v[40:41], 0
	v_mov_b64_e32 v[102:103], 0
	v_mov_b64_e32 v[104:105], 0
	v_mov_b64_e32 v[50:51], 0
	v_mov_b64_e32 v[52:53], 0
	v_mov_b64_e32 v[114:115], 0
	v_mov_b64_e32 v[116:117], 0
	v_mov_b64_e32 v[54:55], 0
	v_mov_b64_e32 v[56:57], 0
	v_mov_b64_e32 v[122:123], 0
	v_mov_b64_e32 v[124:125], 0
	v_mov_b64_e32 v[42:43], 0
	v_mov_b64_e32 v[44:45], 0
	v_mov_b64_e32 v[106:107], 0
	v_mov_b64_e32 v[108:109], 0
	v_mov_b64_e32 v[46:47], 0
	v_mov_b64_e32 v[48:49], 0
	v_mov_b64_e32 v[110:111], 0
	v_mov_b64_e32 v[112:113], 0
	v_mov_b64_e32 v[58:59], 0
	v_mov_b64_e32 v[60:61], 0
	v_mov_b64_e32 v[118:119], 0
	v_mov_b64_e32 v[120:121], 0
	v_mov_b64_e32 v[62:63], 0
	v_mov_b64_e32 v[64:65], 0
	v_mov_b64_e32 v[126:127], 0
	v_mov_b64_e32 v[128:129], 0
	s_cmp_eq_u32 s32, 0
	s_cbranch_scc1 .Lp5_nostag
	s_mov_b32 s32, 0
	s_barrier
.Lp5_nostag:
.LBB0_752:
	s_add_u32 s36, s34, 0xfff80080
	s_addc_u32 s37, s35, -1
	s_add_i32 s61, 0, 0x10000
	s_cmp_eq_u32 s59, 28
	s_cselect_b32 vcc_hi, s1, s37
	s_cselect_b32 vcc_lo, s0, s36
	s_cselect_b32 s37, s63, s17
	s_cselect_b32 s36, s62, s13
	s_add_i32 s64, 0, 0x14000
	v_add_u32_e32 v142, s61, v248
	v_add_u32_e32 v182, s64, v248
	ds_read_b128 v[130:133], v142
	ds_read_b128 v[134:137], v142 offset:1024
	ds_read_b128 v[138:141], v142 offset:2048
	ds_read_b128 v[142:145], v142 offset:3072
	ds_read_b128 v[158:161], v182
	ds_read_b128 v[174:177], v182 offset:1024
	ds_read_b128 v[178:181], v182 offset:2048
	ds_read_b128 v[182:185], v182 offset:3072
	v_lshl_add_u64 v[218:219], s[34:35], 0, v[154:155]
	s_add_i32 m0, s85, 0xc000
	ds_read_b128 v[186:189], v251
	ds_read_b128 v[190:193], v251 offset:1024
	ds_read_b128 v[194:197], v251 offset:2048
	ds_read_b128 v[198:201], v251 offset:3072
	ds_read_b128 v[202:205], v251 offset:4096
	ds_read_b128 v[206:209], v251 offset:5120
	ds_read_b128 v[210:213], v251 offset:6144
	ds_read_b128 v[214:217], v251 offset:7168
	global_load_lds_dwordx4 v[218:219], off
	v_lshl_add_u64 v[218:219], s[34:35], 0, v[156:157]
	s_add_i32 m0, s85, 0xe000
	s_nop 0
	global_load_lds_dwordx4 v[218:219], off
	s_waitcnt vmcnt(8)
	s_waitcnt lgkmcnt(0)
	s_barrier
	s_setprio 1
	s_waitcnt lgkmcnt(0)
	v_mfma_f32_16x16x32_bf16 v[126:129], v[130:133], v[186:189], v[126:129]
	v_mfma_f32_16x16x32_bf16 v[62:65], v[138:141], v[186:189], v[62:65]
	v_mfma_f32_16x16x32_bf16 v[118:121], v[130:133], v[194:197], v[118:121]
	v_mfma_f32_16x16x32_bf16 v[58:61], v[138:141], v[194:197], v[58:61]
	v_mfma_f32_16x16x32_bf16 v[110:113], v[130:133], v[202:205], v[110:113]
	v_mfma_f32_16x16x32_bf16 v[46:49], v[138:141], v[202:205], v[46:49]
	v_mfma_f32_16x16x32_bf16 v[106:109], v[130:133], v[210:213], v[106:109]
	v_mfma_f32_16x16x32_bf16 v[42:45], v[138:141], v[210:213], v[42:45]
	v_mfma_f32_16x16x32_bf16 v[126:129], v[134:137], v[190:193], v[126:129]
	v_mfma_f32_16x16x32_bf16 v[62:65], v[142:145], v[190:193], v[62:65]
	v_mfma_f32_16x16x32_bf16 v[118:121], v[134:137], v[198:201], v[118:121]
	v_mfma_f32_16x16x32_bf16 v[58:61], v[142:145], v[198:201], v[58:61]
	v_mfma_f32_16x16x32_bf16 v[110:113], v[134:137], v[206:209], v[110:113]
	v_mfma_f32_16x16x32_bf16 v[46:49], v[142:145], v[206:209], v[46:49]
	v_mfma_f32_16x16x32_bf16 v[106:109], v[134:137], v[214:217], v[106:109]
	v_mfma_f32_16x16x32_bf16 v[42:45], v[142:145], v[214:217], v[42:45]
	v_mfma_f32_16x16x32_bf16 v[122:125], v[158:161], v[186:189], v[122:125]
	v_mfma_f32_16x16x32_bf16 v[54:57], v[178:181], v[186:189], v[54:57]
	v_mfma_f32_16x16x32_bf16 v[114:117], v[158:161], v[194:197], v[114:117]
	v_mfma_f32_16x16x32_bf16 v[50:53], v[178:181], v[194:197], v[50:53]
	v_mfma_f32_16x16x32_bf16 v[102:105], v[158:161], v[202:205], v[102:105]
	v_mfma_f32_16x16x32_bf16 v[38:41], v[178:181], v[202:205], v[38:41]
	v_mfma_f32_16x16x32_bf16 v[98:101], v[158:161], v[210:213], v[98:101]
	v_mfma_f32_16x16x32_bf16 v[34:37], v[178:181], v[210:213], v[34:37]
	v_mfma_f32_16x16x32_bf16 v[122:125], v[174:177], v[190:193], v[122:125]
	v_mfma_f32_16x16x32_bf16 v[54:57], v[182:185], v[190:193], v[54:57]
	v_mfma_f32_16x16x32_bf16 v[114:117], v[174:177], v[198:201], v[114:117]
	v_mfma_f32_16x16x32_bf16 v[50:53], v[182:185], v[198:201], v[50:53]
	v_mfma_f32_16x16x32_bf16 v[102:105], v[174:177], v[206:209], v[102:105]
	v_mfma_f32_16x16x32_bf16 v[38:41], v[182:185], v[206:209], v[38:41]
	v_mfma_f32_16x16x32_bf16 v[98:101], v[174:177], v[214:217], v[98:101]
	v_mfma_f32_16x16x32_bf16 v[34:37], v[182:185], v[214:217], v[34:37]
	s_setprio 0
	s_barrier
; #define PG8_STAGE(bufoff, gbase, voff) do { _Pragma("unroll") for (int _i = 0; _i < 2; ++_i) \
;         __builtin_amdgcn_global_load_lds((const __attribute__((address_space(1))) unsigned*)((const char*)(gbase) + (voff)[_i]), (LAS unsigned*)(lds + (bufoff) + ldsw + _i * 8192), 16, 0, 0); } while (0)
; #define PG8_LDA(dst, b, h) do { _Pragma("unroll") for (int m = 0; m < 4; ++m) _Pragma("unroll") for (int k = 0; k < 2; ++k) dst[m][k] = *(const LAS bf16x8*)(lds + PG8_SA(b, h) + aoff + m * 2048 + k * 1024); } while (0)
; #define PG8_LDB(dst, b, h) do { _Pragma("unroll") for (int n = 0; n < 2; ++n) _Pragma("unroll") for (int k = 0; k < 2; ++k) dst[n][k] = *(const LAS bf16x8*)(lds + PG8_SB(b, h) + boff + n * 2048 + k * 1024); } while (0)
; #define PG8_MMA(ai, bj, At, Bt) do { __builtin_amdgcn_s_setprio(1); _Pragma("unroll") for (int m = 0; m < 4; ++m) _Pragma("unroll") for (int n = 0; n < 2; ++n) _Pragma("unroll") for (int k = 0; k < 2; ++k) \
;         acc[ai][bj][m][n] = __builtin_amdgcn_mfma_f32_16x16x32_bf16(Bt[n][k], At[m][k], acc[ai][bj][m][n], 0, 0, 0); __builtin_amdgcn_s_setprio(0); } while (0)
; #define PG8_WAIT_V(n) asm volatile("s_waitcnt vmcnt(" #n ")" ::: "memory")
; #define PG8_WAIT_L(n) asm volatile("s_waitcnt lgkmcnt(" #n ")" ::: "memory")
; #define PG8_BAR __builtin_amdgcn_s_barrier()
; #define PG8_SCHED __builtin_amdgcn_sched_barrier(0)
; template <class Epi, class SchedT, bool ALIGN_EPI, bool SP2>
; __device__ __forceinline__ void gemm_phase(LAS unsigned char* lds, const int ldk, const int nt, const SchedT& S, const Epi& E) {
;     ...
;             PG8_LDA(At, 0, 1); PG8_STAGE(PG8_SB(0, 0), b2, voffB); PG8_STAGE(PG8_SB(0, 1), b2 + hstepB, voffB); PG8_STAGE(PG8_SA(0, 0), a2, voffA);
;             PG8_WAIT_V(8); PG8_WAIT_L(0); PG8_BAR; PG8_MMA(1, 0, At, B0); PG8_MMA(1, 1, At, B1); PG8_BAR; PG8_SCHED;
;             PG8_LDB(B0, 1, 0); PG8_LDB(B1, 1, 1); PG8_SCHED; PG8_LDA(At, 1, 0); PG8_STAGE(PG8_SA(0, 1), a2 + hstep, voffA);
	s_add_i32 s61, s61, s84
	v_lshl_add_u64 v[218:219], s[36:37], 0, v[0:1]
	s_mov_b32 m0, s61
	ds_read_b128 v[186:189], v251 offset:16384
	ds_read_b128 v[190:193], v251 offset:17408
	ds_read_b128 v[194:197], v251 offset:18432
	ds_read_b128 v[198:201], v251 offset:19456
	ds_read_b128 v[202:205], v251 offset:20480
	ds_read_b128 v[206:209], v251 offset:21504
	ds_read_b128 v[210:213], v251 offset:22528
	ds_read_b128 v[214:217], v251 offset:23552
	global_load_lds_dwordx4 v[218:219], off
	s_add_i32 m0, s61, 0x2000
	s_add_u32 s94, s36, 0x20000
	v_lshl_add_u64 v[220:221], s[36:37], 0, v[150:151]
	s_addc_u32 s95, s37, 0
	s_add_i32 s61, s64, s84
	global_load_lds_dwordx4 v[220:221], off
	v_lshl_add_u64 v[222:223], s[94:95], 0, v[0:1]
	s_mov_b32 m0, s61
	v_lshl_add_u64 v[224:225], vcc, 0, v[148:149]
	global_load_lds_dwordx4 v[222:223], off
	v_lshl_add_u64 v[222:223], s[94:95], 0, v[150:151]
	s_add_i32 m0, s61, 0x2000
	s_nop 0
	global_load_lds_dwordx4 v[222:223], off
	v_lshl_add_u64 v[222:223], vcc, 0, v[146:147]
	s_mov_b32 m0, s85
	s_nop 0
	global_load_lds_dwordx4 v[222:223], off
	s_mov_b32 m0, s86
	s_nop 0
	global_load_lds_dwordx4 v[224:225], off
	s_waitcnt vmcnt(8)
	s_waitcnt lgkmcnt(0)
	s_barrier
	s_setprio 1
	s_waitcnt lgkmcnt(0)
	v_mfma_f32_16x16x32_bf16 v[94:97], v[130:133], v[186:189], v[94:97]
	v_mfma_f32_16x16x32_bf16 v[30:33], v[138:141], v[186:189], v[30:33]
	v_mfma_f32_16x16x32_bf16 v[90:93], v[130:133], v[194:197], v[90:93]
	v_mfma_f32_16x16x32_bf16 v[26:29], v[138:141], v[194:197], v[26:29]
	v_mfma_f32_16x16x32_bf16 v[78:81], v[130:133], v[202:205], v[78:81]
	v_mfma_f32_16x16x32_bf16 v[14:17], v[138:141], v[202:205], v[14:17]
	v_mfma_f32_16x16x32_bf16 v[74:77], v[130:133], v[210:213], v[74:77]
	v_mfma_f32_16x16x32_bf16 v[10:13], v[138:141], v[210:213], v[10:13]
	v_mfma_f32_16x16x32_bf16 v[94:97], v[134:137], v[190:193], v[94:97]
	v_mfma_f32_16x16x32_bf16 v[30:33], v[142:145], v[190:193], v[30:33]
	v_mfma_f32_16x16x32_bf16 v[90:93], v[134:137], v[198:201], v[90:93]
	v_mfma_f32_16x16x32_bf16 v[26:29], v[142:145], v[198:201], v[26:29]
	v_mfma_f32_16x16x32_bf16 v[78:81], v[134:137], v[206:209], v[78:81]
	v_mfma_f32_16x16x32_bf16 v[14:17], v[142:145], v[206:209], v[14:17]
	v_mfma_f32_16x16x32_bf16 v[74:77], v[134:137], v[214:217], v[74:77]
	v_mfma_f32_16x16x32_bf16 v[10:13], v[142:145], v[214:217], v[10:13]
	v_mfma_f32_16x16x32_bf16 v[86:89], v[158:161], v[186:189], v[86:89]
	v_mfma_f32_16x16x32_bf16 v[22:25], v[178:181], v[186:189], v[22:25]
	v_mfma_f32_16x16x32_bf16 v[82:85], v[158:161], v[194:197], v[82:85]
	v_mfma_f32_16x16x32_bf16 v[18:21], v[178:181], v[194:197], v[18:21]
	v_mfma_f32_16x16x32_bf16 v[70:73], v[158:161], v[202:205], v[70:73]
	v_mfma_f32_16x16x32_bf16 v[6:9], v[178:181], v[202:205], v[6:9]
	v_mfma_f32_16x16x32_bf16 v[66:69], v[158:161], v[210:213], v[66:69]
	v_mfma_f32_16x16x32_bf16 v[2:5], v[178:181], v[210:213], v[2:5]
	v_mfma_f32_16x16x32_bf16 v[86:89], v[174:177], v[190:193], v[86:89]
	v_mfma_f32_16x16x32_bf16 v[22:25], v[182:185], v[190:193], v[22:25]
	v_mfma_f32_16x16x32_bf16 v[82:85], v[174:177], v[198:201], v[82:85]
	v_mfma_f32_16x16x32_bf16 v[18:21], v[182:185], v[198:201], v[18:21]
	v_mfma_f32_16x16x32_bf16 v[70:73], v[174:177], v[206:209], v[70:73]
	v_mfma_f32_16x16x32_bf16 v[6:9], v[182:185], v[206:209], v[6:9]
	v_mfma_f32_16x16x32_bf16 v[66:69], v[174:177], v[214:217], v[66:69]
	v_mfma_f32_16x16x32_bf16 v[2:5], v[182:185], v[214:217], v[2:5]
	s_setprio 0
	s_barrier
	s_add_i32 s61, 0, 0x18000
	s_add_i32 s64, 0, 0x1c000
	v_add_u32_e32 v142, s61, v248
	v_add_u32_e32 v182, s64, v248
	ds_read_b128 v[130:133], v142
	ds_read_b128 v[134:137], v142 offset:1024
	ds_read_b128 v[138:141], v142 offset:2048
	ds_read_b128 v[142:145], v142 offset:3072
	ds_read_b128 v[158:161], v182
	ds_read_b128 v[174:177], v182 offset:1024
	ds_read_b128 v[178:181], v182 offset:2048
	ds_read_b128 v[182:185], v182 offset:3072
	s_add_u32 s94, vcc_lo, 0x80000
	s_addc_u32 s95, vcc_hi, 0
	s_mov_b32 m0, s87
	v_lshl_add_u64 v[226:227], s[94:95], 0, v[146:147]
	ds_read_b128 v[186:189], v251 offset:32768
	ds_read_b128 v[190:193], v251 offset:33792
	ds_read_b128 v[194:197], v251 offset:34816
	ds_read_b128 v[198:201], v251 offset:35840
	ds_read_b128 v[202:205], v251 offset:36864
	ds_read_b128 v[206:209], v251 offset:37888
	ds_read_b128 v[210:213], v251 offset:38912
	ds_read_b128 v[214:217], v251 offset:39936
	global_load_lds_dwordx4 v[226:227], off
	v_lshl_add_u64 v[226:227], s[94:95], 0, v[148:149]
	s_mov_b32 m0, s88
	s_nop 0
	global_load_lds_dwordx4 v[226:227], off
	s_waitcnt vmcnt(8)
	s_waitcnt lgkmcnt(0)
	s_barrier
; #define PG8_STAGE(bufoff, gbase, voff) do { _Pragma("unroll") for (int _i = 0; _i < 2; ++_i) \
;         __builtin_amdgcn_global_load_lds((const __attribute__((address_space(1))) unsigned*)((const char*)(gbase) + (voff)[_i]), (LAS unsigned*)(lds + (bufoff) + ldsw + _i * 8192), 16, 0, 0); } while (0)
; #define PG8_LDA(dst, b, h) do { _Pragma("unroll") for (int m = 0; m < 4; ++m) _Pragma("unroll") for (int k = 0; k < 2; ++k) dst[m][k] = *(const LAS bf16x8*)(lds + PG8_SA(b, h) + aoff + m * 2048 + k * 1024); } while (0)
; #define PG8_LDB(dst, b, h) do { _Pragma("unroll") for (int n = 0; n < 2; ++n) _Pragma("unroll") for (int k = 0; k < 2; ++k) dst[n][k] = *(const LAS bf16x8*)(lds + PG8_SB(b, h) + boff + n * 2048 + k * 1024); } while (0)
; #define PG8_MMA(ai, bj, At, Bt) do { __builtin_amdgcn_s_setprio(1); _Pragma("unroll") for (int m = 0; m < 4; ++m) _Pragma("unroll") for (int n = 0; n < 2; ++n) _Pragma("unroll") for (int k = 0; k < 2; ++k) \
;         acc[ai][bj][m][n] = __builtin_amdgcn_mfma_f32_16x16x32_bf16(Bt[n][k], At[m][k], acc[ai][bj][m][n], 0, 0, 0); __builtin_amdgcn_s_setprio(0); } while (0)
; #define PG8_WAIT_V(n) asm volatile("s_waitcnt vmcnt(" #n ")" ::: "memory")
; #define PG8_WAIT_L(n) asm volatile("s_waitcnt lgkmcnt(" #n ")" ::: "memory")
; #define PG8_BAR __builtin_amdgcn_s_barrier()
; #define PG8_SCHED __builtin_amdgcn_sched_barrier(0)
; template <class Epi, class SchedT, bool ALIGN_EPI, bool SP2>
; __device__ __forceinline__ void gemm_phase(LAS unsigned char* lds, const int ldk, const int nt, const SchedT& S, const Epi& E) {
;     ...
;             PG8_LDB(B0, 1, 0); PG8_LDB(B1, 1, 1); PG8_SCHED; PG8_LDA(At, 1, 0); PG8_STAGE(PG8_SA(0, 1), a2 + hstep, voffA);
;             PG8_WAIT_V(8); PG8_WAIT_L(0); PG8_BAR; PG8_MMA(0, 0, At, B0); PG8_MMA(0, 1, At, B1); PG8_BAR; PG8_SCHED;
;             PG8_LDA(At, 1, 1); PG8_STAGE(PG8_SB(1, 0), b3, voffB); PG8_STAGE(PG8_SB(1, 1), b3 + hstepB, voffB); PG8_STAGE(PG8_SA(1, 0), a3, voffA);
	s_setprio 1
	s_waitcnt lgkmcnt(0)
	v_mfma_f32_16x16x32_bf16 v[126:129], v[130:133], v[186:189], v[126:129]
	v_mfma_f32_16x16x32_bf16 v[62:65], v[138:141], v[186:189], v[62:65]
	v_mfma_f32_16x16x32_bf16 v[118:121], v[130:133], v[194:197], v[118:121]
	v_mfma_f32_16x16x32_bf16 v[58:61], v[138:141], v[194:197], v[58:61]
	v_mfma_f32_16x16x32_bf16 v[110:113], v[130:133], v[202:205], v[110:113]
	v_mfma_f32_16x16x32_bf16 v[46:49], v[138:141], v[202:205], v[46:49]
	v_mfma_f32_16x16x32_bf16 v[106:109], v[130:133], v[210:213], v[106:109]
	v_mfma_f32_16x16x32_bf16 v[42:45], v[138:141], v[210:213], v[42:45]
	v_mfma_f32_16x16x32_bf16 v[126:129], v[134:137], v[190:193], v[126:129]
	v_mfma_f32_16x16x32_bf16 v[62:65], v[142:145], v[190:193], v[62:65]
	v_mfma_f32_16x16x32_bf16 v[118:121], v[134:137], v[198:201], v[118:121]
	v_mfma_f32_16x16x32_bf16 v[58:61], v[142:145], v[198:201], v[58:61]
	v_mfma_f32_16x16x32_bf16 v[110:113], v[134:137], v[206:209], v[110:113]
	v_mfma_f32_16x16x32_bf16 v[46:49], v[142:145], v[206:209], v[46:49]
	v_mfma_f32_16x16x32_bf16 v[106:109], v[134:137], v[214:217], v[106:109]
	v_mfma_f32_16x16x32_bf16 v[42:45], v[142:145], v[214:217], v[42:45]
	v_mfma_f32_16x16x32_bf16 v[122:125], v[158:161], v[186:189], v[122:125]
	v_mfma_f32_16x16x32_bf16 v[54:57], v[178:181], v[186:189], v[54:57]
	v_mfma_f32_16x16x32_bf16 v[114:117], v[158:161], v[194:197], v[114:117]
	v_mfma_f32_16x16x32_bf16 v[50:53], v[178:181], v[194:197], v[50:53]
	v_mfma_f32_16x16x32_bf16 v[102:105], v[158:161], v[202:205], v[102:105]
	v_mfma_f32_16x16x32_bf16 v[38:41], v[178:181], v[202:205], v[38:41]
	v_mfma_f32_16x16x32_bf16 v[98:101], v[158:161], v[210:213], v[98:101]
	v_mfma_f32_16x16x32_bf16 v[34:37], v[178:181], v[210:213], v[34:37]
	v_mfma_f32_16x16x32_bf16 v[122:125], v[174:177], v[190:193], v[122:125]
	v_mfma_f32_16x16x32_bf16 v[54:57], v[182:185], v[190:193], v[54:57]
	v_mfma_f32_16x16x32_bf16 v[114:117], v[174:177], v[198:201], v[114:117]
	v_mfma_f32_16x16x32_bf16 v[50:53], v[182:185], v[198:201], v[50:53]
	v_mfma_f32_16x16x32_bf16 v[102:105], v[174:177], v[206:209], v[102:105]
	v_mfma_f32_16x16x32_bf16 v[38:41], v[182:185], v[206:209], v[38:41]
	v_mfma_f32_16x16x32_bf16 v[98:101], v[174:177], v[214:217], v[98:101]
	v_mfma_f32_16x16x32_bf16 v[34:37], v[182:185], v[214:217], v[34:37]
	s_setprio 0
	s_barrier
	s_add_i32 s61, s61, s84
	v_lshl_add_u64 v[218:219], v[218:219], 0, s[24:25]
	s_mov_b32 m0, s61
	ds_read_b128 v[186:189], v251 offset:49152
	ds_read_b128 v[190:193], v251 offset:50176
	ds_read_b128 v[194:197], v251 offset:51200
	ds_read_b128 v[198:201], v251 offset:52224
	ds_read_b128 v[202:205], v251 offset:53248
	ds_read_b128 v[206:209], v251 offset:54272
	ds_read_b128 v[210:213], v251 offset:55296
	ds_read_b128 v[214:217], v251 offset:56320
	global_load_lds_dwordx4 v[218:219], off
	s_add_i32 m0, s61, 0x2000
	s_add_u32 s36, s36, 0x20080
	v_lshl_add_u64 v[218:219], v[220:221], 0, s[24:25]
	s_addc_u32 s37, s37, 0
	s_add_i32 s61, s64, s84
	global_load_lds_dwordx4 v[218:219], off
	v_lshl_add_u64 v[218:219], s[36:37], 0, v[0:1]
	s_mov_b32 m0, s61
	s_nop 0
	global_load_lds_dwordx4 v[218:219], off
	v_lshl_add_u64 v[218:219], s[36:37], 0, v[150:151]
	s_add_i32 m0, s61, 0x2000
	s_nop 0
	global_load_lds_dwordx4 v[218:219], off
	v_lshl_add_u64 v[218:219], v[222:223], 0, s[24:25]
	s_mov_b32 m0, s89
	s_nop 0
	global_load_lds_dwordx4 v[218:219], off
	v_lshl_add_u64 v[218:219], v[224:225], 0, s[24:25]
	s_mov_b32 m0, s90
	s_nop 0
	global_load_lds_dwordx4 v[218:219], off
	s_waitcnt vmcnt(8)
	s_waitcnt lgkmcnt(0)
	s_barrier
; #define PG8_STAGE(bufoff, gbase, voff) do { _Pragma("unroll") for (int _i = 0; _i < 2; ++_i) \
;         __builtin_amdgcn_global_load_lds((const __attribute__((address_space(1))) unsigned*)((const char*)(gbase) + (voff)[_i]), (LAS unsigned*)(lds + (bufoff) + ldsw + _i * 8192), 16, 0, 0); } while (0)
; #define PG8_LDA(dst, b, h) do { _Pragma("unroll") for (int m = 0; m < 4; ++m) _Pragma("unroll") for (int k = 0; k < 2; ++k) dst[m][k] = *(const LAS bf16x8*)(lds + PG8_SA(b, h) + aoff + m * 2048 + k * 1024); } while (0)
; #define PG8_MMA(ai, bj, At, Bt) do { __builtin_amdgcn_s_setprio(1); _Pragma("unroll") for (int m = 0; m < 4; ++m) _Pragma("unroll") for (int n = 0; n < 2; ++n) _Pragma("unroll") for (int k = 0; k < 2; ++k) \
;         acc[ai][bj][m][n] = __builtin_amdgcn_mfma_f32_16x16x32_bf16(Bt[n][k], At[m][k], acc[ai][bj][m][n], 0, 0, 0); __builtin_amdgcn_s_setprio(0); } while (0)
; #define PG8_WAIT_V(n) asm volatile("s_waitcnt vmcnt(" #n ")" ::: "memory")
; #define PG8_WAIT_L(n) asm volatile("s_waitcnt lgkmcnt(" #n ")" ::: "memory")
; #define PG8_BAR __builtin_amdgcn_s_barrier()
; #define PG8_SCHED __builtin_amdgcn_sched_barrier(0)
; __device__ __forceinline__ float row_rstd(const float* ssp, int row, int fq) {
;     const f32x4 a = *(const f32x4*)(ssp + (size_t)row * 32 + 8 * fq), b = *(const f32x4*)(ssp + (size_t)row * 32 + 8 * fq + 4);
;     float s = ((a[0] + a[1]) + (a[2] + a[3])) + ((b[0] + b[1]) + (b[2] + b[3]));
;     s += __shfl_xor(s, 16); s += __shfl_xor(s, 32);
;     return __builtin_amdgcn_rsqf(s * (1.0f / 2048.0f) + 1e-6f);
; template <class Epi, class SchedT, bool ALIGN_EPI, bool SP2>
; __device__ __forceinline__ void gemm_phase(LAS unsigned char* lds, const int ldk, const int nt, const SchedT& S, const Epi& E) {
;     ...
;             PG8_WAIT_V(8); PG8_WAIT_L(0); PG8_BAR; PG8_MMA(0, 0, At, B0); PG8_MMA(0, 1, At, B1); PG8_BAR; PG8_SCHED;
;             PG8_LDA(At, 1, 1); PG8_STAGE(PG8_SB(1, 0), b3, voffB); PG8_STAGE(PG8_SB(1, 1), b3 + hstepB, voffB); PG8_STAGE(PG8_SA(1, 0), a3, voffA);
;             PG8_WAIT_V(8); PG8_WAIT_L(0); PG8_BAR; PG8_MMA(1, 0, At, B0); PG8_MMA(1, 1, At, B1); PG8_BAR; PG8_SCHED;
	s_setprio 1
	s_waitcnt lgkmcnt(0)
	v_mfma_f32_16x16x32_bf16 v[94:97], v[130:133], v[186:189], v[94:97]
	v_mfma_f32_16x16x32_bf16 v[30:33], v[138:141], v[186:189], v[30:33]
	v_mfma_f32_16x16x32_bf16 v[90:93], v[130:133], v[194:197], v[90:93]
	v_mfma_f32_16x16x32_bf16 v[26:29], v[138:141], v[194:197], v[26:29]
	v_mfma_f32_16x16x32_bf16 v[78:81], v[130:133], v[202:205], v[78:81]
	v_mfma_f32_16x16x32_bf16 v[14:17], v[138:141], v[202:205], v[14:17]
	v_mfma_f32_16x16x32_bf16 v[74:77], v[130:133], v[210:213], v[74:77]
	v_mfma_f32_16x16x32_bf16 v[10:13], v[138:141], v[210:213], v[10:13]
	v_mfma_f32_16x16x32_bf16 v[94:97], v[134:137], v[190:193], v[94:97]
	v_mfma_f32_16x16x32_bf16 v[30:33], v[142:145], v[190:193], v[30:33]
	v_mfma_f32_16x16x32_bf16 v[90:93], v[134:137], v[198:201], v[90:93]
	v_mfma_f32_16x16x32_bf16 v[26:29], v[142:145], v[198:201], v[26:29]
	v_mfma_f32_16x16x32_bf16 v[78:81], v[134:137], v[206:209], v[78:81]
	v_mfma_f32_16x16x32_bf16 v[14:17], v[142:145], v[206:209], v[14:17]
	v_mfma_f32_16x16x32_bf16 v[74:77], v[134:137], v[214:217], v[74:77]
	v_mfma_f32_16x16x32_bf16 v[10:13], v[142:145], v[214:217], v[10:13]
	v_mfma_f32_16x16x32_bf16 v[86:89], v[158:161], v[186:189], v[86:89]
	v_mfma_f32_16x16x32_bf16 v[22:25], v[178:181], v[186:189], v[22:25]
	v_mfma_f32_16x16x32_bf16 v[82:85], v[158:161], v[194:197], v[82:85]
	v_mfma_f32_16x16x32_bf16 v[18:21], v[178:181], v[194:197], v[18:21]
	v_mfma_f32_16x16x32_bf16 v[70:73], v[158:161], v[202:205], v[70:73]
	v_mfma_f32_16x16x32_bf16 v[6:9], v[178:181], v[202:205], v[6:9]
	v_mfma_f32_16x16x32_bf16 v[66:69], v[158:161], v[210:213], v[66:69]
	v_mfma_f32_16x16x32_bf16 v[2:5], v[178:181], v[210:213], v[2:5]
	v_mfma_f32_16x16x32_bf16 v[86:89], v[174:177], v[190:193], v[86:89]
	v_mfma_f32_16x16x32_bf16 v[22:25], v[182:185], v[190:193], v[22:25]
	v_mfma_f32_16x16x32_bf16 v[82:85], v[174:177], v[198:201], v[82:85]
	v_mfma_f32_16x16x32_bf16 v[18:21], v[182:185], v[198:201], v[18:21]
	v_mfma_f32_16x16x32_bf16 v[70:73], v[174:177], v[206:209], v[70:73]
	v_mfma_f32_16x16x32_bf16 v[6:9], v[182:185], v[206:209], v[6:9]
	v_mfma_f32_16x16x32_bf16 v[66:69], v[174:177], v[214:217], v[66:69]
	v_mfma_f32_16x16x32_bf16 v[2:5], v[182:185], v[214:217], v[2:5]
	s_setprio 0
	s_barrier
	s_add_i32 s59, s59, 2
	s_add_u32 s34, s34, 0x100
	s_addc_u32 s35, s35, 0
	s_add_u32 s13, s13, 0x100
	s_addc_u32 s17, s17, 0
	s_cmp_gt_u32 s59, 29
	s_cbranch_scc0 .LBB0_752
	v_lshl_add_u32 v130, s12, 8, v247
	v_lshlrev_b32_e32 v140, 7, v130
	v_mov_b32_e32 v141, 0
	v_lshl_add_u64 v[132:133], v[152:153], 0, v[140:141]
	v_add_u32_e32 v140, 0x1000, v140
	v_lshl_add_u64 v[134:135], v[152:153], 0, v[140:141]
	v_add_u32_e32 v140, 0x3000, v140
	v_lshl_add_u64 v[136:137], v[152:153], 0, v[140:141]
	v_add_u32_e32 v140, 0x1000, v140
	v_lshl_add_u64 v[138:139], v[152:153], 0, v[140:141]
	global_load_dwordx4 v[174:177], v[132:133], off
	global_load_dwordx4 v[178:181], v[132:133], off offset:16
	global_load_dwordx4 v[182:185], v[132:133], off offset:2048
	global_load_dwordx4 v[186:189], v[132:133], off offset:2064
	global_load_dwordx4 v[190:193], v[134:135], off
	global_load_dwordx4 v[194:197], v[134:135], off offset:16
	global_load_dwordx4 v[198:201], v[134:135], off offset:2048
	global_load_dwordx4 v[202:205], v[134:135], off offset:2064
	global_load_dwordx4 v[206:209], v[136:137], off
	global_load_dwordx4 v[210:213], v[136:137], off offset:16
	global_load_dwordx4 v[214:217], v[136:137], off offset:2048
	global_load_dwordx4 v[218:221], v[136:137], off offset:2064
	global_load_dwordx4 v[222:225], v[138:139], off
	global_load_dwordx4 v[226:229], v[138:139], off offset:16
	global_load_dwordx4 v[230:233], v[138:139], off offset:2048
	global_load_dwordx4 v[234:237], v[138:139], off offset:2064
	v_xor_b32_e32 v238, 16, v241
	v_xor_b32_e32 v239, 32, v241
	v_lshlrev_b32_e32 v238, 2, v238
	v_lshlrev_b32_e32 v239, 2, v239
	s_and_b64 vcc, exec, s[56:57]
	s_cbranch_vccz .LBB0_755
	s_barrier
	s_setprio 3

; #define PG8_BAR __builtin_amdgcn_s_barrier()
; template <class Epi, class SchedT, bool ALIGN_EPI, bool SP2>
; __device__ __forceinline__ void gemm_phase(LAS unsigned char* lds, const int ldk, const int nt, const SchedT& S, const Epi& E) {
;     ...
;         cur = nxt; cA = nA; cB = nB; ++ui;
;         if constexpr (ALIGN_EPI) { if (wr == 1) PG8_BAR; }
;     }
.LBB0_788:
	s_cmp_lg_u64 s[52:53], 0
	s_cselect_b32 s32, 1, 0
	s_branch .LBB0_745
